# grid barrier: the XCD leader signals its XCD's generation word before its own L1 invalidate (the invalidate overlaps the other workgroups' wake-up)
# baseline (speedup 1.0000x reference)
; __device__ __forceinline__ unsigned xb_ld(unsigned* p)              { return __hip_atomic_load(p, __ATOMIC_RELAXED, __HIP_MEMORY_SCOPE_AGENT); }
; __device__ __forceinline__ unsigned xb_add(unsigned* p, unsigned v) { return __hip_atomic_fetch_add(p, v, __ATOMIC_RELAXED, __HIP_MEMORY_SCOPE_AGENT); }
; #define XB_SPIN(cond, bar) do { unsigned _sp = 0; while (cond) { __builtin_amdgcn_s_sleep(1); \
;     if ((++_sp & 255u) == 0u) { if (xb_ld(&(bar)[XB_TMO])) break; if (_sp > XB_SPIN_CAP) { atomicAdd(&(bar)[XB_TMO], 1u); break; } } } } while (0)
; __device__ __forceinline__ void xcd_barrier(const XcdBarrier& b) {
;     ...
;             if (og + 1u == (tg + 1u) * nx) xb_add(&bar[XB_TOPGEN], 1u);
;             else XB_SPIN(xb_ld(&bar[XB_TOPGEN]) == tg, bar);
;             __builtin_amdgcn_fence(__ATOMIC_ACQUIRE, "agent");
;             xb_add(&bar[XB_XGEN(b.x)], 1u);
;             asm volatile("s_waitcnt vmcnt(0)" ::: "memory");
.LBB0_82:
	s_or_b64 exec, exec, s[10:11]
	s_mov_b64 s[10:11], exec
	v_mbcnt_lo_u32_b32 v0, s10, 0
	v_mbcnt_hi_u32_b32 v0, s11, v0
	v_cmp_eq_u32_e32 vcc, 0, v0
	s_waitcnt vmcnt(0)
	s_and_saveexec_b64 s[12:13], vcc
	s_cbranch_execz .LBB0_84
	s_bcnt1_i32_b64 s3, s[10:11]
	v_mov_b32_e32 v0, 0x2000
	v_mov_b32_e32 v1, s3
	global_atomic_add v0, v1, s[8:9] offset:1024
.LBB0_84:
	s_or_b64 exec, exec, s[12:13]
	buffer_inv sc1
	s_waitcnt vmcnt(0)

; __device__ __forceinline__ unsigned xb_ld(unsigned* p)              { return __hip_atomic_load(p, __ATOMIC_RELAXED, __HIP_MEMORY_SCOPE_AGENT); }
; __device__ __forceinline__ unsigned xb_add(unsigned* p, unsigned v) { return __hip_atomic_fetch_add(p, v, __ATOMIC_RELAXED, __HIP_MEMORY_SCOPE_AGENT); }
; #define XB_SPIN(cond, bar) do { unsigned _sp = 0; while (cond) { __builtin_amdgcn_s_sleep(1); \
;     if ((++_sp & 255u) == 0u) { if (xb_ld(&(bar)[XB_TMO])) break; if (_sp > XB_SPIN_CAP) { atomicAdd(&(bar)[XB_TMO], 1u); break; } } } } while (0)
; __device__ __forceinline__ void xcd_barrier(const XcdBarrier& b) {
;     ...
;             if (og + 1u == (tg + 1u) * nx) xb_add(&bar[XB_TOPGEN], 1u);
;             else XB_SPIN(xb_ld(&bar[XB_TOPGEN]) == tg, bar);
;             __builtin_amdgcn_fence(__ATOMIC_ACQUIRE, "agent");
;             xb_add(&bar[XB_XGEN(b.x)], 1u);
;             asm volatile("s_waitcnt vmcnt(0)" ::: "memory");
.LBB0_243:
	s_or_b64 exec, exec, s[12:13]
	s_mov_b64 s[12:13], exec
	v_mbcnt_lo_u32_b32 v0, s12, 0
	v_mbcnt_hi_u32_b32 v0, s13, v0
	v_cmp_eq_u32_e32 vcc, 0, v0
	s_waitcnt vmcnt(0)
	s_and_saveexec_b64 s[14:15], vcc
	s_cbranch_execz .LBB0_245
	s_bcnt1_i32_b64 s3, s[12:13]
	v_mov_b32_e32 v0, 0x2000
	v_mov_b32_e32 v1, s3
	global_atomic_add v0, v1, s[10:11] offset:1024
.LBB0_245:
	s_or_b64 exec, exec, s[14:15]
	buffer_inv sc1
	s_waitcnt vmcnt(0)

; __device__ __forceinline__ unsigned xb_ld(unsigned* p)              { return __hip_atomic_load(p, __ATOMIC_RELAXED, __HIP_MEMORY_SCOPE_AGENT); }
; __device__ __forceinline__ unsigned xb_add(unsigned* p, unsigned v) { return __hip_atomic_fetch_add(p, v, __ATOMIC_RELAXED, __HIP_MEMORY_SCOPE_AGENT); }
; #define XB_SPIN(cond, bar) do { unsigned _sp = 0; while (cond) { __builtin_amdgcn_s_sleep(1); \
;     if ((++_sp & 255u) == 0u) { if (xb_ld(&(bar)[XB_TMO])) break; if (_sp > XB_SPIN_CAP) { atomicAdd(&(bar)[XB_TMO], 1u); break; } } } } while (0)
; __device__ __forceinline__ void xcd_barrier(const XcdBarrier& b) {
;     ...
;             if (og + 1u == (tg + 1u) * nx) xb_add(&bar[XB_TOPGEN], 1u);
;             else XB_SPIN(xb_ld(&bar[XB_TOPGEN]) == tg, bar);
;             __builtin_amdgcn_fence(__ATOMIC_ACQUIRE, "agent");
;             xb_add(&bar[XB_XGEN(b.x)], 1u);
;             asm volatile("s_waitcnt vmcnt(0)" ::: "memory");
.LBB0_465:
	s_or_b64 exec, exec, s[12:13]
	s_mov_b64 s[12:13], exec
	v_mbcnt_lo_u32_b32 v0, s12, 0
	v_mbcnt_hi_u32_b32 v0, s13, v0
	v_cmp_eq_u32_e32 vcc, 0, v0
	s_waitcnt vmcnt(0)
	s_and_saveexec_b64 s[14:15], vcc
	s_cbranch_execz .LBB0_467
	s_bcnt1_i32_b64 s4, s[12:13]
	v_mov_b32_e32 v0, 0x2000
	v_mov_b32_e32 v1, s4
	global_atomic_add v0, v1, s[10:11] offset:1024

; __device__ __forceinline__ unsigned xb_ld(unsigned* p)              { return __hip_atomic_load(p, __ATOMIC_RELAXED, __HIP_MEMORY_SCOPE_AGENT); }
; __device__ __forceinline__ unsigned xb_add(unsigned* p, unsigned v) { return __hip_atomic_fetch_add(p, v, __ATOMIC_RELAXED, __HIP_MEMORY_SCOPE_AGENT); }
; #define XB_SPIN(cond, bar) do { unsigned _sp = 0; while (cond) { __builtin_amdgcn_s_sleep(1); \
;     if ((++_sp & 255u) == 0u) { if (xb_ld(&(bar)[XB_TMO])) break; if (_sp > XB_SPIN_CAP) { atomicAdd(&(bar)[XB_TMO], 1u); break; } } } } while (0)
; __device__ __forceinline__ void xcd_barrier(const XcdBarrier& b) {
;     ...
;             if (og + 1u == (tg + 1u) * nx) xb_add(&bar[XB_TOPGEN], 1u);
;             else XB_SPIN(xb_ld(&bar[XB_TOPGEN]) == tg, bar);
;             __builtin_amdgcn_fence(__ATOMIC_ACQUIRE, "agent");
;             xb_add(&bar[XB_XGEN(b.x)], 1u);
;             asm volatile("s_waitcnt vmcnt(0)" ::: "memory");
.LBB0_825:
	s_or_b64 exec, exec, s[14:15]
	s_mov_b64 s[14:15], exec
	v_mbcnt_lo_u32_b32 v0, s14, 0
	v_mbcnt_hi_u32_b32 v0, s15, v0
	v_cmp_eq_u32_e32 vcc, 0, v0
	s_waitcnt vmcnt(0)
	s_and_saveexec_b64 s[20:21], vcc
	s_cbranch_execz .LBB0_827
	s_bcnt1_i32_b64 s4, s[14:15]
	v_mov_b32_e32 v0, 0x2000
	v_mov_b32_e32 v1, s4
	global_atomic_add v0, v1, s[12:13] offset:1024
.LBB0_827:
	s_or_b64 exec, exec, s[20:21]
	buffer_inv sc1
	s_waitcnt vmcnt(0)

; __device__ __forceinline__ unsigned xb_ld(unsigned* p)              { return __hip_atomic_load(p, __ATOMIC_RELAXED, __HIP_MEMORY_SCOPE_AGENT); }
; __device__ __forceinline__ unsigned xb_add(unsigned* p, unsigned v) { return __hip_atomic_fetch_add(p, v, __ATOMIC_RELAXED, __HIP_MEMORY_SCOPE_AGENT); }
; #define XB_SPIN(cond, bar) do { unsigned _sp = 0; while (cond) { __builtin_amdgcn_s_sleep(1); \
;     if ((++_sp & 255u) == 0u) { if (xb_ld(&(bar)[XB_TMO])) break; if (_sp > XB_SPIN_CAP) { atomicAdd(&(bar)[XB_TMO], 1u); break; } } } } while (0)
; __device__ __forceinline__ void xcd_barrier(const XcdBarrier& b) {
;     ...
;             __builtin_amdgcn_fence(__ATOMIC_RELEASE, "agent");
;             asm volatile("s_waitcnt vmcnt(0)" ::: "memory");
;             const unsigned og = xb_add(&bar[XB_TOP], 1u);
;             const unsigned tg = og / nx;
;             if (og + 1u == (tg + 1u) * nx) xb_add(&bar[XB_TOPGEN], 1u);
;             else XB_SPIN(xb_ld(&bar[XB_TOPGEN]) == tg, bar);
;             __builtin_amdgcn_fence(__ATOMIC_ACQUIRE, "agent");
;             xb_add(&bar[XB_XGEN(b.x)], 1u);
;             asm volatile("s_waitcnt vmcnt(0)" ::: "memory");
.LBB0_914:
	s_or_b64 exec, exec, s[14:15]
	s_mov_b64 s[14:15], exec
	v_mbcnt_lo_u32_b32 v0, s14, 0
	v_mbcnt_hi_u32_b32 v0, s15, v0
	v_cmp_eq_u32_e32 vcc, 0, v0
	s_waitcnt vmcnt(0)
	s_and_saveexec_b64 s[18:19], vcc
	s_cbranch_execz .LBB0_916
	s_bcnt1_i32_b64 s4, s[14:15]
	v_mov_b32_e32 v0, 0x2000
	v_mov_b32_e32 v1, s4
	global_atomic_add v0, v1, s[12:13] offset:1024
.LBB0_916:
	s_or_b64 exec, exec, s[18:19]
	buffer_inv sc1
	s_waitcnt vmcnt(0)

; __device__ __forceinline__ unsigned xb_ld(unsigned* p)              { return __hip_atomic_load(p, __ATOMIC_RELAXED, __HIP_MEMORY_SCOPE_AGENT); }
; __device__ __forceinline__ unsigned xb_add(unsigned* p, unsigned v) { return __hip_atomic_fetch_add(p, v, __ATOMIC_RELAXED, __HIP_MEMORY_SCOPE_AGENT); }
; #define XB_SPIN(cond, bar) do { unsigned _sp = 0; while (cond) { __builtin_amdgcn_s_sleep(1); \
;     if ((++_sp & 255u) == 0u) { if (xb_ld(&(bar)[XB_TMO])) break; if (_sp > XB_SPIN_CAP) { atomicAdd(&(bar)[XB_TMO], 1u); break; } } } } while (0)
; __device__ __forceinline__ void xcd_barrier(const XcdBarrier& b) {
;     ...
;             __builtin_amdgcn_fence(__ATOMIC_RELEASE, "agent");
;             asm volatile("s_waitcnt vmcnt(0)" ::: "memory");
;             const unsigned og = xb_add(&bar[XB_TOP], 1u);
;             const unsigned tg = og / nx;
;             if (og + 1u == (tg + 1u) * nx) xb_add(&bar[XB_TOPGEN], 1u);
;             else XB_SPIN(xb_ld(&bar[XB_TOPGEN]) == tg, bar);
;             __builtin_amdgcn_fence(__ATOMIC_ACQUIRE, "agent");
;             xb_add(&bar[XB_XGEN(b.x)], 1u);
;             asm volatile("s_waitcnt vmcnt(0)" ::: "memory");
.LBB0_1069:
	s_or_b64 exec, exec, s[16:17]
	s_mov_b64 s[16:17], exec
	v_mbcnt_lo_u32_b32 v0, s16, 0
	v_mbcnt_hi_u32_b32 v0, s17, v0
	v_cmp_eq_u32_e32 vcc, 0, v0
	s_waitcnt vmcnt(0)
	s_and_saveexec_b64 s[26:27], vcc
	s_cbranch_execz .LBB0_1071
	s_bcnt1_i32_b64 s4, s[16:17]
	v_mov_b32_e32 v0, 0x2000
	v_mov_b32_e32 v1, s4
	global_atomic_add v0, v1, s[14:15] offset:1024
.LBB0_1071:
	s_or_b64 exec, exec, s[26:27]
	buffer_inv sc1
	s_waitcnt vmcnt(0)

; __device__ __forceinline__ unsigned xb_ld(unsigned* p)              { return __hip_atomic_load(p, __ATOMIC_RELAXED, __HIP_MEMORY_SCOPE_AGENT); }
; __device__ __forceinline__ unsigned xb_add(unsigned* p, unsigned v) { return __hip_atomic_fetch_add(p, v, __ATOMIC_RELAXED, __HIP_MEMORY_SCOPE_AGENT); }
; #define XB_SPIN(cond, bar) do { unsigned _sp = 0; while (cond) { __builtin_amdgcn_s_sleep(1); \
;     if ((++_sp & 255u) == 0u) { if (xb_ld(&(bar)[XB_TMO])) break; if (_sp > XB_SPIN_CAP) { atomicAdd(&(bar)[XB_TMO], 1u); break; } } } } while (0)
; __device__ __forceinline__ void xcd_barrier(const XcdBarrier& b) {
;     ...
;             __builtin_amdgcn_fence(__ATOMIC_RELEASE, "agent");
;             asm volatile("s_waitcnt vmcnt(0)" ::: "memory");
;             const unsigned og = xb_add(&bar[XB_TOP], 1u);
;             const unsigned tg = og / nx;
;             if (og + 1u == (tg + 1u) * nx) xb_add(&bar[XB_TOPGEN], 1u);
;             else XB_SPIN(xb_ld(&bar[XB_TOPGEN]) == tg, bar);
;             __builtin_amdgcn_fence(__ATOMIC_ACQUIRE, "agent");
;             xb_add(&bar[XB_XGEN(b.x)], 1u);
;             asm volatile("s_waitcnt vmcnt(0)" ::: "memory");
.LBB0_1152:
	s_or_b64 exec, exec, s[14:15]
	s_mov_b64 s[14:15], exec
	v_mbcnt_lo_u32_b32 v0, s14, 0
	v_mbcnt_hi_u32_b32 v0, s15, v0
	v_cmp_eq_u32_e32 vcc, 0, v0
	s_waitcnt vmcnt(0)
	s_and_saveexec_b64 s[16:17], vcc
	s_cbranch_execz .LBB0_1154
	s_bcnt1_i32_b64 s4, s[14:15]
	v_mov_b32_e32 v0, 0x2000
	v_mov_b32_e32 v1, s4
	global_atomic_add v0, v1, s[12:13] offset:1024
.LBB0_1154:
	s_or_b64 exec, exec, s[16:17]
	buffer_inv sc1
	s_waitcnt vmcnt(0)

; __device__ __forceinline__ unsigned xb_ld(unsigned* p)              { return __hip_atomic_load(p, __ATOMIC_RELAXED, __HIP_MEMORY_SCOPE_AGENT); }
; __device__ __forceinline__ unsigned xb_add(unsigned* p, unsigned v) { return __hip_atomic_fetch_add(p, v, __ATOMIC_RELAXED, __HIP_MEMORY_SCOPE_AGENT); }
; #define XB_SPIN(cond, bar) do { unsigned _sp = 0; while (cond) { __builtin_amdgcn_s_sleep(1); \
;     if ((++_sp & 255u) == 0u) { if (xb_ld(&(bar)[XB_TMO])) break; if (_sp > XB_SPIN_CAP) { atomicAdd(&(bar)[XB_TMO], 1u); break; } } } } while (0)
; __device__ __forceinline__ void xcd_barrier(const XcdBarrier& b) {
;     ...
;             __builtin_amdgcn_fence(__ATOMIC_RELEASE, "agent");
;             asm volatile("s_waitcnt vmcnt(0)" ::: "memory");
;             const unsigned og = xb_add(&bar[XB_TOP], 1u);
;             const unsigned tg = og / nx;
;             if (og + 1u == (tg + 1u) * nx) xb_add(&bar[XB_TOPGEN], 1u);
;             else XB_SPIN(xb_ld(&bar[XB_TOPGEN]) == tg, bar);
;             __builtin_amdgcn_fence(__ATOMIC_ACQUIRE, "agent");
;             xb_add(&bar[XB_XGEN(b.x)], 1u);
;             asm volatile("s_waitcnt vmcnt(0)" ::: "memory");
.LBB0_1426:
	s_or_b64 exec, exec, s[14:15]
	s_mov_b64 s[14:15], exec
	v_mbcnt_lo_u32_b32 v0, s14, 0
	v_mbcnt_hi_u32_b32 v0, s15, v0
	v_cmp_eq_u32_e32 vcc, 0, v0
	s_waitcnt vmcnt(0)
	s_and_saveexec_b64 s[24:25], vcc
	s_cbranch_execz .LBB0_1428
	s_bcnt1_i32_b64 s4, s[14:15]
	v_mov_b32_e32 v0, 0x2000
	v_mov_b32_e32 v1, s4
	global_atomic_add v0, v1, s[12:13] offset:1024
.LBB0_1428:
	s_or_b64 exec, exec, s[24:25]
	buffer_inv sc1
	s_waitcnt vmcnt(0)

; __device__ __forceinline__ unsigned xb_ld(unsigned* p)              { return __hip_atomic_load(p, __ATOMIC_RELAXED, __HIP_MEMORY_SCOPE_AGENT); }
; __device__ __forceinline__ unsigned xb_add(unsigned* p, unsigned v) { return __hip_atomic_fetch_add(p, v, __ATOMIC_RELAXED, __HIP_MEMORY_SCOPE_AGENT); }
; #define XB_SPIN(cond, bar) do { unsigned _sp = 0; while (cond) { __builtin_amdgcn_s_sleep(1); \
;     if ((++_sp & 255u) == 0u) { if (xb_ld(&(bar)[XB_TMO])) break; if (_sp > XB_SPIN_CAP) { atomicAdd(&(bar)[XB_TMO], 1u); break; } } } } while (0)
; __device__ __forceinline__ void xcd_barrier(const XcdBarrier& b) {
;     ...
;             __builtin_amdgcn_fence(__ATOMIC_RELEASE, "agent");
;             asm volatile("s_waitcnt vmcnt(0)" ::: "memory");
;             const unsigned og = xb_add(&bar[XB_TOP], 1u);
;             const unsigned tg = og / nx;
;             if (og + 1u == (tg + 1u) * nx) xb_add(&bar[XB_TOPGEN], 1u);
;             else XB_SPIN(xb_ld(&bar[XB_TOPGEN]) == tg, bar);
;             __builtin_amdgcn_fence(__ATOMIC_ACQUIRE, "agent");
;             xb_add(&bar[XB_XGEN(b.x)], 1u);
;             asm volatile("s_waitcnt vmcnt(0)" ::: "memory");
.LBB0_2007:
	s_or_b64 exec, exec, s[8:9]
	s_mov_b64 s[8:9], exec
	v_mbcnt_lo_u32_b32 v0, s8, 0
	v_mbcnt_hi_u32_b32 v0, s9, v0
	v_cmp_eq_u32_e32 vcc, 0, v0
	s_waitcnt vmcnt(0)
	s_and_saveexec_b64 s[10:11], vcc
	s_cbranch_execz .LBB0_2009
	s_bcnt1_i32_b64 s4, s[8:9]
	v_mov_b32_e32 v0, 0x2000
	v_mov_b32_e32 v1, s4
	global_atomic_add v0, v1, s[6:7] offset:1024
.LBB0_2009:
	s_or_b64 exec, exec, s[10:11]
	buffer_inv sc1
	s_waitcnt vmcnt(0)
